# plus phase-4 merge output: 16 dwordx2 stores per lane merged into 8 dwordx4 (permlane16 swap)
# speedup vs baseline: 1.0106x; 1.0050x over previous
; DI void phase_merge(const Params& P, int l, char* smem) {
;     ...
; #pragma unroll
;     for (int mt = 0; mt < 4; ++mt) {
;       const int row = row0 + mt * 16 + lr;
; #pragma unroll
;       for (int nt = 0; nt < 4; ++nt)
;         *(uint2*)(MB + (size_t)row * DM + col0 + nt * 16 + 4 * g) = make_uint2(tot[mt][nt][0], tot[mt][nt][1]);
;     }
.LBB0_1156:
	v_or_b32_e32 v8, s12, v110
	v_add_u32_e32 v0, s11, v111
	v_ashrrev_i32_e32 v1, 31, v0
	v_lshlrev_b32_e32 v150, 1, v8
	v_or_b32_e32 v2, 16, v0
	v_or_b32_e32 v4, 32, v0
	v_or_b32_e32 v6, 48, v0
	v_lshl_add_u64 v[8:9], v[60:61], 0, v[150:151]
	v_lshlrev_b64 v[0:1], 11, v[0:1]
	v_ashrrev_i32_e32 v3, 31, v2
	v_lshl_add_u64 v[0:1], v[8:9], 0, v[0:1]
	v_mov_b32_e32 v76, v102
	v_mov_b32_e32 v77, v103
	v_mov_b32_e32 v78, v100
	v_mov_b32_e32 v79, v101
	v_and_b32_e32 v108, 16, v148
	v_lshrrev_b32_e32 v109, 1, v108
	v_add_u32_e32 v108, v108, v109
	v_mov_b32_e32 v109, 0
	v_lshl_add_u64 v[108:109], v[108:109], 0, v[0:1]
	v_permlane16_swap_b32_e32 v76, v78
	v_permlane16_swap_b32_e32 v77, v79
	global_store_dwordx4 v[108:109], v[76:79], off
	v_mov_b32_e32 v80, v98
	v_mov_b32_e32 v81, v99
	v_mov_b32_e32 v82, v96
	v_mov_b32_e32 v83, v97
	v_and_b32_e32 v108, 16, v148
	v_lshrrev_b32_e32 v109, 1, v108
	v_add_u32_e32 v108, v108, v109
	v_mov_b32_e32 v109, 0
	v_lshl_add_u64 v[108:109], v[108:109], 0, v[0:1]
	v_permlane16_swap_b32_e32 v80, v82
	v_permlane16_swap_b32_e32 v81, v83
	global_store_dwordx4 v[108:109], v[80:83], off offset:64
	v_lshlrev_b64 v[0:1], 11, v[2:3]
	v_ashrrev_i32_e32 v5, 31, v4
	v_lshl_add_u64 v[0:1], v[8:9], 0, v[0:1]
	v_mov_b32_e32 v76, v94
	v_mov_b32_e32 v77, v95
	v_mov_b32_e32 v78, v92
	v_mov_b32_e32 v79, v93
	v_and_b32_e32 v108, 16, v148
	v_lshrrev_b32_e32 v109, 1, v108
	v_add_u32_e32 v108, v108, v109
	v_mov_b32_e32 v109, 0
	v_lshl_add_u64 v[108:109], v[108:109], 0, v[0:1]
	v_permlane16_swap_b32_e32 v76, v78
	v_permlane16_swap_b32_e32 v77, v79
	global_store_dwordx4 v[108:109], v[76:79], off
	v_mov_b32_e32 v80, v90
	v_mov_b32_e32 v81, v91
	v_mov_b32_e32 v82, v88
	v_mov_b32_e32 v83, v89
	v_and_b32_e32 v108, 16, v148
	v_lshrrev_b32_e32 v109, 1, v108
	v_add_u32_e32 v108, v108, v109
	v_mov_b32_e32 v109, 0
	v_lshl_add_u64 v[108:109], v[108:109], 0, v[0:1]
	v_permlane16_swap_b32_e32 v80, v82
	v_permlane16_swap_b32_e32 v81, v83
	global_store_dwordx4 v[108:109], v[80:83], off offset:64
	v_lshlrev_b64 v[0:1], 11, v[4:5]
	v_ashrrev_i32_e32 v7, 31, v6
	v_lshl_add_u64 v[0:1], v[8:9], 0, v[0:1]
	v_mov_b32_e32 v76, v86
	v_mov_b32_e32 v77, v87
	v_mov_b32_e32 v78, v84
	v_mov_b32_e32 v79, v85
	v_and_b32_e32 v108, 16, v148
	v_lshrrev_b32_e32 v109, 1, v108
	v_add_u32_e32 v108, v108, v109
	v_mov_b32_e32 v109, 0
	v_lshl_add_u64 v[108:109], v[108:109], 0, v[0:1]
	v_permlane16_swap_b32_e32 v76, v78
	v_permlane16_swap_b32_e32 v77, v79
	global_store_dwordx4 v[108:109], v[76:79], off
	v_mov_b32_e32 v80, v74
	v_mov_b32_e32 v81, v75
	v_mov_b32_e32 v82, v72
	v_mov_b32_e32 v83, v73
	v_and_b32_e32 v108, 16, v148
	v_lshrrev_b32_e32 v109, 1, v108
	v_add_u32_e32 v108, v108, v109
	v_mov_b32_e32 v109, 0
	v_lshl_add_u64 v[108:109], v[108:109], 0, v[0:1]
	v_permlane16_swap_b32_e32 v80, v82
	v_permlane16_swap_b32_e32 v81, v83
	global_store_dwordx4 v[108:109], v[80:83], off offset:64
	v_lshlrev_b64 v[0:1], 11, v[6:7]
	v_lshl_add_u64 v[0:1], v[8:9], 0, v[0:1]
	v_mov_b32_e32 v76, v70
	v_mov_b32_e32 v77, v71
	v_mov_b32_e32 v78, v68
	v_mov_b32_e32 v79, v69
	v_and_b32_e32 v108, 16, v148
	v_lshrrev_b32_e32 v109, 1, v108
	v_add_u32_e32 v108, v108, v109
	v_mov_b32_e32 v109, 0
	v_lshl_add_u64 v[108:109], v[108:109], 0, v[0:1]
	v_permlane16_swap_b32_e32 v76, v78
	v_permlane16_swap_b32_e32 v77, v79
	global_store_dwordx4 v[108:109], v[76:79], off
	v_mov_b32_e32 v80, v66
	v_mov_b32_e32 v81, v67
	v_mov_b32_e32 v82, v64
	v_mov_b32_e32 v83, v65
	v_and_b32_e32 v108, 16, v148
	v_lshrrev_b32_e32 v109, 1, v108
	v_add_u32_e32 v108, v108, v109
	v_mov_b32_e32 v109, 0
	v_lshl_add_u64 v[108:109], v[108:109], 0, v[0:1]
	v_permlane16_swap_b32_e32 v80, v82
	v_permlane16_swap_b32_e32 v81, v83
	global_store_dwordx4 v[108:109], v[80:83], off offset:64
